# P2 fused-norm epilogue: residual x loads prefetched 3 row-groups ahead into free VGPRs (counted waits), original loads become moves
# speedup vs baseline: 1.0058x; 1.0058x over previous
; __device__ __forceinline__ float bflo(unsigned w) { return __uint_as_float(w << 16); }
; __device__ __forceinline__ float bfhi(unsigned w) { return __uint_as_float(w & 0xffff0000u); }
; __device__ __forceinline__ unsigned pk2(float lo, float hi) { f32x2 v = {lo, hi}; bf16x2_t b = __builtin_convertvector(v, bf16x2_t); return __builtin_bit_cast(unsigned, b); }
;     __device__ __forceinline__ void fused(f32x4 (&acc)[2][2][4][2], const Unit& u, int wr, int wc, int fr, int fq, LAS unsigned char* lds, int wid, int lane) const {
;     ...
;         stats(acc, u, wr, wc, fr, fq, lds, wid, lane, 0, coef);
; #pragma unroll
;         for (int bj = 0; bj < 2; ++bj) {
;             const int col = u.pn * BM + bj * HALF + wc * 32 + 8 * fq;
;             const f32x4 g0 = *(const f32x4*)(gpost + col), g1 = *(const f32x4*)(gpost + col + 4);
; #pragma unroll
;             for (int ai = 0; ai < 2; ++ai)
; #pragma unroll
;                 for (int m = 0; m < 4; ++m) {
;                     const int rl = ai * HALF + wr * 64 + m * 16 + fr; const size_t off = (size_t)(u.pm * BM + rl) * 1024 + col; const float r = S[rl];
;                     f32x4 x0, x1;
;                     if constexpr (SRC == 0) { x0 = *(const f32x4*)(xin + off); x1 = *(const f32x4*)(xin + off + 4); }
;                     else { const u32x4 w = *(const u32x4*)((SRC == 1 ? XR : XN) + off); x0 = (f32x4){bflo(w.x), bfhi(w.x), bflo(w.y), bfhi(w.y)}; x1 = (f32x4){bflo(w.z), bfhi(w.z), bflo(w.w), bfhi(w.w)}; }
;                     x0 = x0 + acc[ai][bj][m][0] * g0 * r; x1 = x1 + acc[ai][bj][m][1] * g1 * r;
;                     acc[ai][bj][m][0] = x0; acc[ai][bj][m][1] = x1;
;                     if constexpr (NEXT == 0) { *(f32x4*)(Y + off) = x0; *(f32x4*)(Y + off + 4) = x1; }
;                     else { u32x4 w; w.x = pk2(x0[0], x0[1]); w.y = pk2(x0[2], x0[3]); w.z = pk2(x1[0], x1[1]); w.w = pk2(x1[2], x1[3]); *(u32x4*)((NEXT == 1 ? XR : XN) + off) = w; }
;                 }
;         }
.LBB0_341:
	s_or_b64 exec, exec, s[22:23]
	s_add_u32 s8, s0, 0xdc00000
	s_addc_u32 s9, s1, 0
	v_mov_b32_e32 v128, s12
	s_lshl_b32 s11, s39, 5
	s_lshl_b32 s12, s10, 8
	v_lshrrev_b32_e32 v130, 1, v152
	s_or_b32 s11, s12, s11
	v_lshl_add_u32 v148, s16, 8, v153
	v_and_or_b32 v146, v130, 24, s11
	v_ashrrev_i32_e32 v149, 31, v148
	v_mov_b32_e32 v129, s13
	v_ashrrev_i32_e32 v147, 31, v146
	v_lshlrev_b64 v[160:161], 10, v[148:149]
	s_waitcnt vmcnt(0) lgkmcnt(0)
	s_barrier
	v_lshl_add_u64 v[158:159], v[146:147], 2, v[128:129]
	v_lshl_add_u64 v[154:155], v[160:161], 0, v[146:147]
	global_load_dwordx4 v[128:131], v[158:159], off offset:16
	global_load_dwordx4 v[132:135], v[158:159], off
	v_lshl_add_u64 v[162:163], v[154:155], 2, s[18:19]
	global_load_dwordx4 v[140:143], v[162:163], off
	global_load_dwordx4 v[136:139], v[162:163], off offset:16
	s_mov_b32 s98, 0x10000
	s_mov_b32 s99, 0
	v_lshl_add_u64 v[252:253], v[162:163], 0, s[98:99]
	global_load_dwordx4 v[228:231], v[252:253], off
	global_load_dwordx4 v[232:235], v[252:253], off offset:16
	s_mov_b32 s98, 0x20000
	s_mov_b32 s99, 0
	v_lshl_add_u64 v[252:253], v[162:163], 0, s[98:99]
	global_load_dwordx4 v[236:239], v[252:253], off
	global_load_dwordx4 v[240:243], v[252:253], off offset:16
	s_mov_b32 s98, 0x30000
	s_mov_b32 s99, 0
	v_lshl_add_u64 v[252:253], v[162:163], 0, s[98:99]
	global_load_dwordx4 v[244:247], v[252:253], off
	global_load_dwordx4 v[248:251], v[252:253], off offset:16
	v_lshl_add_u32 v165, v153, 2, 0
	ds_read_b32 v156, v165 offset:4096
	s_waitcnt vmcnt(0)
	ds_read_b32 v164, v165 offset:4800
	v_add_u32_e32 v152, 16, v148
	v_ashrrev_i32_e32 v153, 31, v152
	v_lshlrev_b64 v[176:177], 10, v[152:153]
	v_lshl_add_u64 v[168:169], v[176:177], 0, v[146:147]
	v_lshl_add_u64 v[154:155], v[154:155], 1, s[8:9]
	v_lshl_add_u64 v[178:179], v[168:169], 2, s[18:19]
	v_add_u32_e32 v226, 0x1000, v165
	v_pk_mul_f32 v[170:171], v[122:123], v[130:131]
	v_pk_mul_f32 v[126:127], v[126:127], v[134:135]
	v_pk_mul_f32 v[124:125], v[124:125], v[132:133]
	v_pk_mul_f32 v[172:173], v[120:121], v[128:129]
	s_waitcnt lgkmcnt(1)
	v_pk_fma_f32 v[122:123], v[126:127], v[156:157], v[142:143] op_sel_hi:[1,0,1]
	v_pk_fma_f32 v[126:127], v[124:125], v[156:157], v[140:141] op_sel_hi:[1,0,1]
	v_pk_fma_f32 v[120:121], v[170:171], v[156:157], v[138:139] op_sel_hi:[1,0,1]
	v_pk_fma_f32 v[124:125], v[172:173], v[156:157], v[136:137] op_sel_hi:[1,0,1]
	v_cvt_pk_bf16_f32 v136, v126, v127
	v_cvt_pk_bf16_f32 v137, v122, v123
	v_cvt_pk_bf16_f32 v138, v124, v125
	v_cvt_pk_bf16_f32 v139, v120, v121
	global_store_dwordx4 v[154:155], v[136:139], off
	s_nop 1
	s_waitcnt vmcnt(5)
	v_mov_b64_e32 v[136:137], v[228:229]
	v_mov_b64_e32 v[138:139], v[230:231]
	v_mov_b64_e32 v[140:141], v[232:233]
	v_mov_b64_e32 v[142:143], v[234:235]
	s_mov_b32 s98, 0x80000
	s_mov_b32 s99, 0
	v_lshl_add_u64 v[252:253], v[162:163], 0, s[98:99]
	global_load_dwordx4 v[228:231], v[252:253], off
	global_load_dwordx4 v[232:235], v[252:253], off offset:16
	ds_read2_b32 v[180:181], v226 offset1:16
	v_add_u32_e32 v156, 32, v148
	v_ashrrev_i32_e32 v157, 31, v156
	v_lshl_add_u64 v[154:155], v[168:169], 1, s[8:9]
	v_pk_mul_f32 v[118:119], v[118:119], v[134:135]
	s_waitcnt lgkmcnt(0)
	v_mov_b32_e32 v168, v181
	v_pk_mul_f32 v[116:117], v[116:117], v[132:133]
	v_pk_mul_f32 v[172:173], v[114:115], v[130:131]
	v_pk_mul_f32 v[174:175], v[112:113], v[128:129]
	v_lshlrev_b64 v[182:183], 10, v[156:157]
	v_lshl_add_u64 v[170:171], v[182:183], 0, v[146:147]
	v_lshl_add_u64 v[184:185], v[170:171], 2, s[18:19]
	v_pk_mul_f32 v[110:111], v[110:111], v[134:135]
	v_pk_mul_f32 v[106:107], v[106:107], v[130:131]
	v_pk_mul_f32 v[104:105], v[104:105], v[128:129]
	v_pk_mul_f32 v[102:103], v[102:103], v[134:135]
	v_pk_mul_f32 v[100:101], v[100:101], v[132:133]
	v_pk_mul_f32 v[98:99], v[98:99], v[130:131]
	v_pk_mul_f32 v[96:97], v[96:97], v[128:129]
	v_pk_mul_f32 v[94:95], v[94:95], v[134:135]
	v_pk_mul_f32 v[92:93], v[92:93], v[132:133]
	v_pk_mul_f32 v[90:91], v[90:91], v[130:131]
	v_pk_mul_f32 v[88:89], v[88:89], v[128:129]
	v_pk_mul_f32 v[78:79], v[78:79], v[134:135]
	v_pk_mul_f32 v[76:77], v[76:77], v[132:133]
	v_pk_mul_f32 v[74:75], v[74:75], v[130:131]
	v_pk_mul_f32 v[72:73], v[72:73], v[128:129]
	v_pk_mul_f32 v[62:63], v[62:63], v[134:135]
	v_pk_mul_f32 v[222:223], v[60:61], v[132:133]
	v_pk_mul_f32 v[54:55], v[54:55], v[130:131]
	v_pk_mul_f32 v[224:225], v[52:53], v[128:129]
	v_pk_mul_f32 v[46:47], v[46:47], v[134:135]
	v_pk_mul_f32 v[38:39], v[38:39], v[130:131]
	v_pk_mul_f32 v[128:129], v[36:37], v[128:129]
	v_pk_fma_f32 v[114:115], v[118:119], v[168:169], v[138:139] op_sel_hi:[1,0,1]
	v_pk_fma_f32 v[118:119], v[116:117], v[168:169], v[136:137] op_sel_hi:[1,0,1]
	v_pk_fma_f32 v[112:113], v[172:173], v[168:169], v[142:143] op_sel_hi:[1,0,1]
	v_pk_fma_f32 v[116:117], v[174:175], v[168:169], v[140:141] op_sel_hi:[1,0,1]
	v_cvt_pk_bf16_f32 v136, v118, v119
	v_cvt_pk_bf16_f32 v137, v114, v115
	v_cvt_pk_bf16_f32 v138, v116, v117
	v_cvt_pk_bf16_f32 v139, v112, v113
	global_store_dwordx4 v[154:155], v[136:139], off
	s_nop 1
	s_waitcnt vmcnt(6)
	v_mov_b64_e32 v[136:137], v[236:237]
	v_mov_b64_e32 v[138:139], v[238:239]
	v_mov_b64_e32 v[140:141], v[240:241]
	v_mov_b64_e32 v[142:143], v[242:243]
	s_mov_b32 s98, 0x90000
	s_mov_b32 s99, 0
	v_lshl_add_u64 v[252:253], v[162:163], 0, s[98:99]
	global_load_dwordx4 v[236:239], v[252:253], off
	global_load_dwordx4 v[240:243], v[252:253], off offset:16
	ds_read2_b32 v[186:187], v226 offset0:16 offset1:32
	v_add_u32_e32 v154, 48, v148
	v_ashrrev_i32_e32 v155, 31, v154
	v_lshl_add_u64 v[168:169], v[170:171], 1, s[8:9]
	v_pk_mul_f32 v[174:175], v[108:109], v[132:133]
	s_waitcnt lgkmcnt(0)
; __device__ __forceinline__ float bflo(unsigned w) { return __uint_as_float(w << 16); }
; __device__ __forceinline__ float bfhi(unsigned w) { return __uint_as_float(w & 0xffff0000u); }
; __device__ __forceinline__ unsigned pk2(float lo, float hi) { f32x2 v = {lo, hi}; bf16x2_t b = __builtin_convertvector(v, bf16x2_t); return __builtin_bit_cast(unsigned, b); }
;     __device__ __forceinline__ void fused(f32x4 (&acc)[2][2][4][2], const Unit& u, int wr, int wc, int fr, int fq, LAS unsigned char* lds, int wid, int lane) const {
;     ...
;             for (int ai = 0; ai < 2; ++ai)
; #pragma unroll
;                 for (int m = 0; m < 4; ++m) {
;                     const int rl = ai * HALF + wr * 64 + m * 16 + fr; const size_t off = (size_t)(u.pm * BM + rl) * 1024 + col; const float r = S[rl];
;                     f32x4 x0, x1;
;                     if constexpr (SRC == 0) { x0 = *(const f32x4*)(xin + off); x1 = *(const f32x4*)(xin + off + 4); }
;                     else { const u32x4 w = *(const u32x4*)((SRC == 1 ? XR : XN) + off); x0 = (f32x4){bflo(w.x), bfhi(w.x), bflo(w.y), bfhi(w.y)}; x1 = (f32x4){bflo(w.z), bfhi(w.z), bflo(w.w), bfhi(w.w)}; }
;                     x0 = x0 + acc[ai][bj][m][0] * g0 * r; x1 = x1 + acc[ai][bj][m][1] * g1 * r;
;                     acc[ai][bj][m][0] = x0; acc[ai][bj][m][1] = x1;
;                     if constexpr (NEXT == 0) { *(f32x4*)(Y + off) = x0; *(f32x4*)(Y + off + 4) = x1; }
;                     else { u32x4 w; w.x = pk2(x0[0], x0[1]); w.y = pk2(x0[2], x0[3]); w.z = pk2(x1[0], x1[1]); w.w = pk2(x1[2], x1[3]); *(u32x4*)((NEXT == 1 ? XR : XN) + off) = w; }
;                 }
	v_mov_b32_e32 v170, v187
	v_lshlrev_b64 v[188:189], 10, v[154:155]
	v_lshl_add_u64 v[172:173], v[188:189], 0, v[146:147]
	v_lshl_add_u64 v[190:191], v[172:173], 2, s[18:19]
	v_lshl_add_u64 v[172:173], v[172:173], 1, s[8:9]
	v_pk_mul_f32 v[132:133], v[44:45], v[132:133]
	v_pk_fma_f32 v[108:109], v[110:111], v[170:171], v[138:139] op_sel_hi:[1,0,1]
	v_pk_fma_f32 v[136:137], v[174:175], v[170:171], v[136:137] op_sel_hi:[1,0,1]
	v_pk_fma_f32 v[106:107], v[106:107], v[170:171], v[142:143] op_sel_hi:[1,0,1]
	v_pk_fma_f32 v[110:111], v[104:105], v[170:171], v[140:141] op_sel_hi:[1,0,1]
	v_cvt_pk_bf16_f32 v138, v136, v137
	v_cvt_pk_bf16_f32 v139, v108, v109
	v_cvt_pk_bf16_f32 v140, v110, v111
	v_cvt_pk_bf16_f32 v141, v106, v107
	global_store_dwordx4 v[168:169], v[138:141], off
	s_nop 1
	s_waitcnt vmcnt(7)
	v_mov_b64_e32 v[138:139], v[244:245]
	v_mov_b64_e32 v[140:141], v[246:247]
	v_mov_b64_e32 v[168:169], v[248:249]
	v_mov_b64_e32 v[170:171], v[250:251]
	s_mov_b32 s98, 0xa0000
	s_mov_b32 s99, 0
	v_lshl_add_u64 v[252:253], v[162:163], 0, s[98:99]
	global_load_dwordx4 v[244:247], v[252:253], off
	global_load_dwordx4 v[248:251], v[252:253], off offset:16
	ds_read2_b32 v[192:193], v226 offset0:32 offset1:48
	v_add_u32_e32 v104, 0x80, v148
	v_ashrrev_i32_e32 v105, 31, v104
	v_lshlrev_b64 v[194:195], 10, v[104:105]
	v_lshl_add_u64 v[142:143], v[194:195], 0, v[146:147]
	s_waitcnt lgkmcnt(0)
	v_mov_b32_e32 v174, v193
	v_lshl_add_u64 v[196:197], v[142:143], 2, s[18:19]
	v_lshl_add_u64 v[202:203], v[142:143], 1, s[8:9]
	v_pk_fma_f32 v[102:103], v[102:103], v[174:175], v[140:141] op_sel_hi:[1,0,1]
	v_pk_fma_f32 v[140:141], v[100:101], v[174:175], v[138:139] op_sel_hi:[1,0,1]
	v_pk_fma_f32 v[100:101], v[98:99], v[174:175], v[170:171] op_sel_hi:[1,0,1]
	v_pk_fma_f32 v[138:139], v[96:97], v[174:175], v[168:169] op_sel_hi:[1,0,1]
	v_cvt_pk_bf16_f32 v96, v140, v141
	v_cvt_pk_bf16_f32 v97, v102, v103
	v_cvt_pk_bf16_f32 v98, v138, v139
	v_cvt_pk_bf16_f32 v99, v100, v101
	global_store_dwordx4 v[172:173], v[96:99], off
	s_nop 1
	s_waitcnt vmcnt(7)
	v_mov_b64_e32 v[168:169], v[228:229]
	v_mov_b64_e32 v[170:171], v[230:231]
	v_mov_b64_e32 v[172:173], v[232:233]
	v_mov_b64_e32 v[174:175], v[234:235]
	s_mov_b32 s98, 0xb0000
	s_mov_b32 s99, 0
	v_lshl_add_u64 v[252:253], v[162:163], 0, s[98:99]
	global_load_dwordx4 v[228:231], v[252:253], off
	global_load_dwordx4 v[232:235], v[252:253], off offset:16
	ds_read2_b32 v[198:199], v226 offset0:48 offset1:128
	v_add_u32_e32 v96, 0x90, v148
	v_ashrrev_i32_e32 v97, 31, v96
	v_lshlrev_b64 v[200:201], 10, v[96:97]
	v_lshl_add_u64 v[98:99], v[200:201], 0, v[146:147]
	s_waitcnt lgkmcnt(0)
	v_mov_b32_e32 v206, v199
	v_lshl_add_u64 v[204:205], v[98:99], 2, s[18:19]
	v_lshl_add_u64 v[210:211], v[98:99], 1, s[8:9]
	v_pk_fma_f32 v[142:143], v[94:95], v[206:207], v[170:171] op_sel_hi:[1,0,1]
	v_pk_fma_f32 v[94:95], v[92:93], v[206:207], v[168:169] op_sel_hi:[1,0,1]
	v_pk_fma_f32 v[90:91], v[90:91], v[206:207], v[174:175] op_sel_hi:[1,0,1]
	v_pk_fma_f32 v[92:93], v[88:89], v[206:207], v[172:173] op_sel_hi:[1,0,1]
	v_cvt_pk_bf16_f32 v168, v94, v95
	v_cvt_pk_bf16_f32 v169, v142, v143
	v_cvt_pk_bf16_f32 v170, v92, v93
	v_cvt_pk_bf16_f32 v171, v90, v91
	global_store_dwordx4 v[202:203], v[168:171], off
	s_nop 1
	s_waitcnt vmcnt(7)
	v_mov_b64_e32 v[168:169], v[236:237]
	v_mov_b64_e32 v[170:171], v[238:239]
	v_mov_b64_e32 v[172:173], v[240:241]
	v_mov_b64_e32 v[174:175], v[242:243]
	global_load_dwordx4 v[236:239], v[162:163], off offset:512
	global_load_dwordx4 v[240:243], v[162:163], off offset:528
	ds_read2_b32 v[202:203], v226 offset0:128 offset1:144
	v_add_u32_e32 v88, 0xa0, v148
	v_ashrrev_i32_e32 v89, 31, v88
	v_lshlrev_b64 v[206:207], 10, v[88:89]
	v_lshl_add_u64 v[208:209], v[206:207], 0, v[146:147]
	s_waitcnt lgkmcnt(0)
	v_mov_b32_e32 v214, v203
	v_lshl_add_u64 v[212:213], v[208:209], 2, s[18:19]
	v_lshl_add_u64 v[208:209], v[208:209], 1, s[8:9]
	v_pk_fma_f32 v[78:79], v[78:79], v[214:215], v[170:171] op_sel_hi:[1,0,1]
	v_pk_fma_f32 v[98:99], v[76:77], v[214:215], v[168:169] op_sel_hi:[1,0,1]
	v_pk_fma_f32 v[74:75], v[74:75], v[214:215], v[174:175] op_sel_hi:[1,0,1]
	v_pk_fma_f32 v[76:77], v[72:73], v[214:215], v[172:173] op_sel_hi:[1,0,1]
	v_cvt_pk_bf16_f32 v168, v98, v99
	v_cvt_pk_bf16_f32 v169, v78, v79
	v_cvt_pk_bf16_f32 v170, v76, v77
	v_cvt_pk_bf16_f32 v171, v74, v75
	global_store_dwordx4 v[210:211], v[168:171], off
	s_nop 1
	s_waitcnt vmcnt(7)
	v_mov_b64_e32 v[168:169], v[244:245]
	v_mov_b64_e32 v[170:171], v[246:247]
	v_mov_b64_e32 v[172:173], v[248:249]
	v_mov_b64_e32 v[174:175], v[250:251]
	global_load_dwordx4 v[244:247], v[178:179], off offset:512
	global_load_dwordx4 v[248:251], v[178:179], off offset:528
	ds_read2_b32 v[210:211], v226 offset0:144 offset1:160
	v_add_u32_e32 v72, 0xb0, v148
	v_ashrrev_i32_e32 v73, 31, v72
	v_lshlrev_b64 v[214:215], 10, v[72:73]
	v_lshl_add_u64 v[216:217], v[214:215], 0, v[146:147]
	s_waitcnt lgkmcnt(0)
	v_mov_b32_e32 v218, v211
	v_lshl_add_u64 v[220:221], v[216:217], 2, s[18:19]
	v_lshl_add_u64 v[216:217], v[216:217], 1, s[8:9]
	v_pk_fma_f32 v[60:61], v[62:63], v[218:219], v[170:171] op_sel_hi:[1,0,1]
	v_pk_fma_f32 v[62:63], v[222:223], v[218:219], v[168:169] op_sel_hi:[1,0,1]
	v_pk_fma_f32 v[52:53], v[54:55], v[218:219], v[174:175] op_sel_hi:[1,0,1]
	v_pk_fma_f32 v[54:55], v[224:225], v[218:219], v[172:173] op_sel_hi:[1,0,1]
	v_cvt_pk_bf16_f32 v168, v62, v63
	v_cvt_pk_bf16_f32 v169, v60, v61
	v_cvt_pk_bf16_f32 v170, v54, v55
	v_cvt_pk_bf16_f32 v171, v52, v53
	global_store_dwordx4 v[208:209], v[168:171], off
	s_nop 1
	s_waitcnt vmcnt(7)
; __device__ __forceinline__ float bflo(unsigned w) { return __uint_as_float(w << 16); }
; __device__ __forceinline__ float bfhi(unsigned w) { return __uint_as_float(w & 0xffff0000u); }
; __device__ __forceinline__ unsigned pk2(float lo, float hi) { f32x2 v = {lo, hi}; bf16x2_t b = __builtin_convertvector(v, bf16x2_t); return __builtin_bit_cast(unsigned, b); }
;     __device__ __forceinline__ void fused(f32x4 (&acc)[2][2][4][2], const Unit& u, int wr, int wc, int fr, int fq, LAS unsigned char* lds, int wid, int lane) const {
;     ...
; #pragma unroll
;         for (int bj = 0; bj < 2; ++bj) {
;             const int col = u.pn * BM + bj * HALF + wc * 32 + 8 * fq;
;             const f32x4 g0 = *(const f32x4*)(gpost + col), g1 = *(const f32x4*)(gpost + col + 4);
; #pragma unroll
;             for (int ai = 0; ai < 2; ++ai)
; #pragma unroll
;                 for (int m = 0; m < 4; ++m) {
;                     const int rl = ai * HALF + wr * 64 + m * 16 + fr; const size_t off = (size_t)(u.pm * BM + rl) * 1024 + col; const float r = S[rl];
;                     f32x4 x0, x1;
;                     if constexpr (SRC == 0) { x0 = *(const f32x4*)(xin + off); x1 = *(const f32x4*)(xin + off + 4); }
;                     else { const u32x4 w = *(const u32x4*)((SRC == 1 ? XR : XN) + off); x0 = (f32x4){bflo(w.x), bfhi(w.x), bflo(w.y), bfhi(w.y)}; x1 = (f32x4){bflo(w.z), bfhi(w.z), bflo(w.w), bfhi(w.w)}; }
;                     x0 = x0 + acc[ai][bj][m][0] * g0 * r; x1 = x1 + acc[ai][bj][m][1] * g1 * r;
;                     acc[ai][bj][m][0] = x0; acc[ai][bj][m][1] = x1;
;                     if constexpr (NEXT == 0) { *(f32x4*)(Y + off) = x0; *(f32x4*)(Y + off + 4) = x1; }
;                     else { u32x4 w; w.x = pk2(x0[0], x0[1]); w.y = pk2(x0[2], x0[3]); w.z = pk2(x1[0], x1[1]); w.w = pk2(x1[2], x1[3]); *(u32x4*)((NEXT == 1 ? XR : XN) + off) = w; }
;                 }
;         }
	v_mov_b64_e32 v[168:169], v[228:229]
	v_mov_b64_e32 v[170:171], v[230:231]
	v_mov_b64_e32 v[172:173], v[232:233]
	v_mov_b64_e32 v[174:175], v[234:235]
	global_load_dwordx4 v[228:231], v[184:185], off offset:512
	global_load_dwordx4 v[232:235], v[184:185], off offset:528
	ds_read2_b32 v[208:209], v226 offset0:160 offset1:176
	s_waitcnt lgkmcnt(0)
	v_mov_b32_e32 v218, v209
	v_pk_fma_f32 v[44:45], v[46:47], v[218:219], v[170:171] op_sel_hi:[1,0,1]
	v_pk_fma_f32 v[46:47], v[132:133], v[218:219], v[168:169] op_sel_hi:[1,0,1]
	v_pk_fma_f32 v[36:37], v[38:39], v[218:219], v[174:175] op_sel_hi:[1,0,1]
	v_pk_fma_f32 v[38:39], v[128:129], v[218:219], v[172:173] op_sel_hi:[1,0,1]
	v_cvt_pk_bf16_f32 v128, v46, v47
	v_cvt_pk_bf16_f32 v129, v44, v45
	v_cvt_pk_bf16_f32 v130, v38, v39
	v_cvt_pk_bf16_f32 v131, v36, v37
	global_store_dwordx4 v[216:217], v[128:131], off
	global_load_dwordx4 v[128:131], v[158:159], off offset:512
	s_nop 0
	global_load_dwordx4 v[132:135], v[158:159], off offset:528
	s_waitcnt vmcnt(9)
	v_mov_b64_e32 v[168:169], v[236:237]
	v_mov_b64_e32 v[170:171], v[238:239]
	v_mov_b64_e32 v[172:173], v[240:241]
	v_mov_b64_e32 v[174:175], v[242:243]
	global_load_dwordx4 v[236:239], v[190:191], off offset:512
	global_load_dwordx4 v[240:243], v[190:191], off offset:528
	v_or_b32_e32 v162, 0x80, v146
	v_ashrrev_i32_e32 v163, 31, v162
	v_lshl_add_u64 v[158:159], v[160:161], 0, v[162:163]
	v_lshl_add_u64 v[216:217], v[158:159], 1, s[8:9]
	s_waitcnt vmcnt(2)
	v_pk_mul_f32 v[86:87], v[86:87], v[130:131]
	v_pk_mul_f32 v[84:85], v[84:85], v[128:129]
	v_pk_mul_f32 v[158:159], v[82:83], v[134:135]
	v_pk_mul_f32 v[160:161], v[80:81], v[132:133]
	v_pk_fma_f32 v[82:83], v[86:87], v[180:181], v[170:171] op_sel_hi:[1,0,1]
	v_pk_fma_f32 v[86:87], v[84:85], v[180:181], v[168:169] op_sel_hi:[1,0,1]
	v_pk_fma_f32 v[80:81], v[158:159], v[180:181], v[174:175] op_sel_hi:[1,0,1]
	v_pk_fma_f32 v[84:85], v[160:161], v[180:181], v[172:173] op_sel_hi:[1,0,1]
	v_cvt_pk_bf16_f32 v158, v86, v87
	v_cvt_pk_bf16_f32 v159, v82, v83
	v_cvt_pk_bf16_f32 v160, v84, v85
	v_cvt_pk_bf16_f32 v161, v80, v81
	global_store_dwordx4 v[216:217], v[158:161], off
	s_nop 1
	s_waitcnt vmcnt(9)
	v_mov_b64_e32 v[158:159], v[244:245]
	v_mov_b64_e32 v[160:161], v[246:247]
	v_mov_b64_e32 v[168:169], v[248:249]
	v_mov_b64_e32 v[170:171], v[250:251]
	global_load_dwordx4 v[244:247], v[196:197], off offset:512
	global_load_dwordx4 v[248:251], v[196:197], off offset:528
	v_lshl_add_u64 v[172:173], v[176:177], 0, v[162:163]
	v_pk_mul_f32 v[70:71], v[70:71], v[130:131]
	v_pk_mul_f32 v[174:175], v[68:69], v[128:129]
	v_pk_mul_f32 v[66:67], v[66:67], v[134:135]
	v_pk_mul_f32 v[176:177], v[64:65], v[132:133]
	v_lshl_add_u64 v[172:173], v[172:173], 1, s[8:9]
	v_pk_mul_f32 v[58:59], v[58:59], v[130:131]
	v_pk_mul_f32 v[50:51], v[50:51], v[134:135]
	v_pk_mul_f32 v[42:43], v[42:43], v[130:131]
	v_pk_mul_f32 v[34:35], v[34:35], v[134:135]
	v_pk_mul_f32 v[30:31], v[30:31], v[130:131]
	v_pk_mul_f32 v[26:27], v[26:27], v[134:135]
	v_pk_mul_f32 v[22:23], v[22:23], v[130:131]
	v_pk_mul_f32 v[18:19], v[18:19], v[134:135]
	v_pk_mul_f32 v[14:15], v[14:15], v[130:131]
	v_pk_mul_f32 v[10:11], v[10:11], v[134:135]
	v_pk_mul_f32 v[6:7], v[6:7], v[130:131]
	v_pk_mul_f32 v[130:131], v[0:1], v[132:133]
	v_mul_f32_e32 v0, v87, v87
	v_mul_f32_e32 v1, v83, v83
	v_pk_mul_f32 v[4:5], v[4:5], v[128:129]
	v_fmac_f32_e32 v0, v86, v86
	v_fmac_f32_e32 v1, v82, v82
	v_add_f32_e32 v0, v0, v1
	v_pk_mul_f32 v[2:3], v[2:3], v[134:135]
	v_pk_fma_f32 v[68:69], v[70:71], v[186:187], v[160:161] op_sel_hi:[1,0,1]
	v_pk_fma_f32 v[70:71], v[174:175], v[186:187], v[158:159] op_sel_hi:[1,0,1]
	v_pk_fma_f32 v[64:65], v[66:67], v[186:187], v[170:171] op_sel_hi:[1,0,1]
	v_pk_fma_f32 v[66:67], v[176:177], v[186:187], v[168:169] op_sel_hi:[1,0,1]
	v_cvt_pk_bf16_f32 v158, v70, v71
	v_cvt_pk_bf16_f32 v159, v68, v69
	v_cvt_pk_bf16_f32 v160, v66, v67
	v_cvt_pk_bf16_f32 v161, v64, v65
	global_store_dwordx4 v[172:173], v[158:161], off
	s_nop 1
	s_waitcnt vmcnt(9)
	v_mov_b64_e32 v[158:159], v[228:229]
	v_mov_b64_e32 v[160:161], v[230:231]
	v_mov_b64_e32 v[168:169], v[232:233]
	v_mov_b64_e32 v[170:171], v[234:235]
	global_load_dwordx4 v[228:231], v[204:205], off offset:512
	global_load_dwordx4 v[232:235], v[204:205], off offset:528
	v_pk_mul_f32 v[174:175], v[56:57], v[128:129]
	v_pk_mul_f32 v[176:177], v[48:49], v[132:133]
	v_lshl_add_u64 v[172:173], v[182:183], 0, v[162:163]
	v_lshl_add_u64 v[172:173], v[172:173], 1, s[8:9]
	v_pk_fma_f32 v[56:57], v[58:59], v[192:193], v[160:161] op_sel_hi:[1,0,1]
	v_pk_fma_f32 v[58:59], v[174:175], v[192:193], v[158:159] op_sel_hi:[1,0,1]
	v_pk_fma_f32 v[48:49], v[50:51], v[192:193], v[170:171] op_sel_hi:[1,0,1]
	v_pk_fma_f32 v[50:51], v[176:177], v[192:193], v[168:169] op_sel_hi:[1,0,1]
	v_cvt_pk_bf16_f32 v158, v58, v59
	v_cvt_pk_bf16_f32 v159, v56, v57
	v_cvt_pk_bf16_f32 v160, v50, v51
	v_cvt_pk_bf16_f32 v161, v48, v49
	global_store_dwordx4 v[172:173], v[158:161], off
	s_nop 1
	s_waitcnt vmcnt(7)
	v_mov_b64_e32 v[158:159], v[236:237]
	v_mov_b64_e32 v[160:161], v[238:239]
	v_mov_b64_e32 v[168:169], v[240:241]
	v_mov_b64_e32 v[170:171], v[242:243]
	global_load_dwordx4 v[236:239], v[212:213], off offset:512
	global_load_dwordx4 v[240:243], v[212:213], off offset:528
	v_pk_mul_f32 v[174:175], v[40:41], v[128:129]
	v_pk_mul_f32 v[176:177], v[32:33], v[132:133]
	v_lshl_add_u64 v[172:173], v[188:189], 0, v[162:163]
	v_lshl_add_u64 v[172:173], v[172:173], 1, s[8:9]
	v_pk_fma_f32 v[40:41], v[42:43], v[198:199], v[160:161] op_sel_hi:[1,0,1]
	v_pk_fma_f32 v[42:43], v[174:175], v[198:199], v[158:159] op_sel_hi:[1,0,1]
	v_pk_fma_f32 v[32:33], v[34:35], v[198:199], v[170:171] op_sel_hi:[1,0,1]
	v_pk_fma_f32 v[34:35], v[176:177], v[198:199], v[168:169] op_sel_hi:[1,0,1]
	v_cvt_pk_bf16_f32 v158, v42, v43
	v_cvt_pk_bf16_f32 v159, v40, v41
	v_cvt_pk_bf16_f32 v160, v34, v35
	v_cvt_pk_bf16_f32 v161, v32, v33
	global_store_dwordx4 v[172:173], v[158:161], off
	s_nop 1
	s_waitcnt vmcnt(7)
;     __device__ __forceinline__ void stats(const f32x4 (&v)[2][2][4][2], const Unit& u, int wr, int wc, int fr, int fq, LAS unsigned char* lds, int wid, int lane, int which, float c) const {
;     ...
; #pragma unroll
;         for (int ai = 0; ai < 2; ++ai)
; #pragma unroll
;             for (int m = 0; m < 4; ++m) { float q = 0.f;
; #pragma unroll
;                 for (int bj = 0; bj < 2; ++bj)
; #pragma unroll
;                     for (int n = 0; n < 2; ++n) { const f32x4 x = v[ai][bj][m][n]; q += (x[0] * x[0] + x[1] * x[1]) + (x[2] * x[2] + x[3] * x[3]); }
;                 { const unsigned uq = __float_as_uint(q); const auto r_ = __builtin_amdgcn_permlane16_swap(uq, uq, false, false); q = __uint_as_float(r_[0]) + __uint_as_float(r_[1]); }
;                 { const unsigned uq = __float_as_uint(q); const auto r_ = __builtin_amdgcn_permlane32_swap(uq, uq, false, false); q = __uint_as_float(r_[0]) + __uint_as_float(r_[1]); }
;     __device__ __forceinline__ void fused(f32x4 (&acc)[2][2][4][2], const Unit& u, int wr, int wc, int fr, int fq, LAS unsigned char* lds, int wid, int lane) const {
;     ...
;             for (int ai = 0; ai < 2; ++ai)
; #pragma unroll
;                 for (int m = 0; m < 4; ++m) {
;                     const int rl = ai * HALF + wr * 64 + m * 16 + fr; const size_t off = (size_t)(u.pm * BM + rl) * 1024 + col; const float r = S[rl];
;                     f32x4 x0, x1;
;                     if constexpr (SRC == 0) { x0 = *(const f32x4*)(xin + off); x1 = *(const f32x4*)(xin + off + 4); }
;                     else { const u32x4 w = *(const u32x4*)((SRC == 1 ? XR : XN) + off); x0 = (f32x4){bflo(w.x), bfhi(w.x), bflo(w.y), bfhi(w.y)}; x1 = (f32x4){bflo(w.z), bfhi(w.z), bflo(w.w), bfhi(w.w)}; }
;                     x0 = x0 + acc[ai][bj][m][0] * g0 * r; x1 = x1 + acc[ai][bj][m][1] * g1 * r;
;                     acc[ai][bj][m][0] = x0; acc[ai][bj][m][1] = x1;
;                     if constexpr (NEXT == 0) { *(f32x4*)(Y + off) = x0; *(f32x4*)(Y + off + 4) = x1; }
;                     else { u32x4 w; w.x = pk2(x0[0], x0[1]); w.y = pk2(x0[2], x0[3]); w.z = pk2(x1[0], x1[1]); w.w = pk2(x1[2], x1[3]); *(u32x4*)((NEXT == 1 ? XR : XN) + off) = w; }
;                 }
;         }
;         if constexpr (NEXT == 1) {
;             stats(acc, u, wr, wc, fr, fq, lds, wid, lane, 1, 1.f);
	v_mov_b64_e32 v[158:159], v[244:245]
	v_mov_b64_e32 v[160:161], v[246:247]
	v_mov_b64_e32 v[168:169], v[248:249]
	v_mov_b64_e32 v[170:171], v[250:251]
	global_load_dwordx4 v[244:247], v[220:221], off offset:512
	global_load_dwordx4 v[248:251], v[220:221], off offset:528
	v_pk_mul_f32 v[174:175], v[28:29], v[128:129]
	v_pk_mul_f32 v[176:177], v[24:25], v[132:133]
	v_lshl_add_u64 v[172:173], v[194:195], 0, v[162:163]
	v_lshl_add_u64 v[172:173], v[172:173], 1, s[8:9]
	v_pk_fma_f32 v[28:29], v[30:31], v[202:203], v[160:161] op_sel_hi:[1,0,1]
	v_pk_fma_f32 v[30:31], v[174:175], v[202:203], v[158:159] op_sel_hi:[1,0,1]
	v_pk_fma_f32 v[24:25], v[26:27], v[202:203], v[170:171] op_sel_hi:[1,0,1]
	v_pk_fma_f32 v[26:27], v[176:177], v[202:203], v[168:169] op_sel_hi:[1,0,1]
	v_cvt_pk_bf16_f32 v158, v30, v31
	v_cvt_pk_bf16_f32 v159, v28, v29
	v_cvt_pk_bf16_f32 v160, v26, v27
	v_cvt_pk_bf16_f32 v161, v24, v25
	global_store_dwordx4 v[172:173], v[158:161], off
	s_nop 1
	s_waitcnt vmcnt(7)
	v_mov_b64_e32 v[158:159], v[228:229]
	v_mov_b64_e32 v[160:161], v[230:231]
	v_mov_b64_e32 v[168:169], v[232:233]
	v_mov_b64_e32 v[170:171], v[234:235]
	v_pk_mul_f32 v[174:175], v[20:21], v[128:129]
	v_pk_mul_f32 v[176:177], v[16:17], v[132:133]
	v_lshl_add_u64 v[172:173], v[200:201], 0, v[162:163]
	v_lshl_add_u64 v[172:173], v[172:173], 1, s[8:9]
	v_pk_fma_f32 v[20:21], v[22:23], v[210:211], v[160:161] op_sel_hi:[1,0,1]
	v_pk_fma_f32 v[22:23], v[174:175], v[210:211], v[158:159] op_sel_hi:[1,0,1]
	v_pk_fma_f32 v[16:17], v[18:19], v[210:211], v[170:171] op_sel_hi:[1,0,1]
	v_pk_fma_f32 v[18:19], v[176:177], v[210:211], v[168:169] op_sel_hi:[1,0,1]
	v_cvt_pk_bf16_f32 v158, v22, v23
	v_cvt_pk_bf16_f32 v159, v20, v21
	v_cvt_pk_bf16_f32 v160, v18, v19
	v_cvt_pk_bf16_f32 v161, v16, v17
	global_store_dwordx4 v[172:173], v[158:161], off
	s_nop 1
	s_waitcnt vmcnt(5)
	v_mov_b64_e32 v[158:159], v[236:237]
	v_mov_b64_e32 v[160:161], v[238:239]
	v_mov_b64_e32 v[168:169], v[240:241]
	v_mov_b64_e32 v[170:171], v[242:243]
	v_pk_mul_f32 v[174:175], v[12:13], v[128:129]
	v_pk_mul_f32 v[176:177], v[8:9], v[132:133]
	v_lshl_add_u64 v[172:173], v[206:207], 0, v[162:163]
	v_lshl_add_u64 v[172:173], v[172:173], 1, s[8:9]
	v_mul_f32_e32 v128, v85, v85
	v_mul_f32_e32 v129, v81, v81
	v_fmac_f32_e32 v128, v84, v84
	v_fmac_f32_e32 v129, v80, v80
	v_add_f32_e32 v1, v128, v129
	v_lshl_add_u64 v[162:163], v[214:215], 0, v[162:163]
	v_lshl_add_u64 v[162:163], v[162:163], 1, s[8:9]
	v_pk_fma_f32 v[12:13], v[14:15], v[208:209], v[160:161] op_sel_hi:[1,0,1]
	v_pk_fma_f32 v[14:15], v[174:175], v[208:209], v[158:159] op_sel_hi:[1,0,1]
	v_pk_fma_f32 v[8:9], v[10:11], v[208:209], v[170:171] op_sel_hi:[1,0,1]
	v_pk_fma_f32 v[10:11], v[176:177], v[208:209], v[168:169] op_sel_hi:[1,0,1]
	v_cvt_pk_bf16_f32 v158, v14, v15
	v_cvt_pk_bf16_f32 v159, v12, v13
	v_cvt_pk_bf16_f32 v160, v10, v11
	v_cvt_pk_bf16_f32 v161, v8, v9
	global_store_dwordx4 v[172:173], v[158:161], off
	s_nop 1
	s_waitcnt vmcnt(3)
	v_mov_b64_e32 v[158:159], v[244:245]
	v_mov_b64_e32 v[160:161], v[246:247]
	v_mov_b64_e32 v[168:169], v[248:249]
	v_mov_b64_e32 v[170:171], v[250:251]
	v_mul_f32_e32 v172, v127, v127
	v_mul_f32_e32 v173, v123, v123
	v_mul_f32_e32 v174, v125, v125
	v_mul_f32_e32 v175, v121, v121
	v_fmac_f32_e32 v172, v126, v126
	v_fmac_f32_e32 v173, v122, v122
	v_fmac_f32_e32 v174, v124, v124
	v_fmac_f32_e32 v175, v120, v120
	v_add_f32_e32 v172, v172, v173
	v_add_f32_e32 v173, v174, v175
	v_add_f32_e32 v172, v172, v173
	v_add_f32_e32 v0, v172, v0
	v_add_f32_e32 v0, v1, v0
	v_mov_b32_e32 v1, v0
	s_nop 1
	v_permlane16_swap_b32_e32 v0, v1
	v_add_f32_e32 v0, v0, v1
	v_mov_b32_e32 v1, v0
	s_nop 1
	v_permlane32_swap_b32_e32 v0, v1
	v_pk_fma_f32 v[132:133], v[6:7], v[164:165], v[160:161] op_sel_hi:[1,0,1]
	v_pk_fma_f32 v[134:135], v[4:5], v[164:165], v[158:159] op_sel_hi:[1,0,1]
	v_pk_fma_f32 v[128:129], v[2:3], v[164:165], v[170:171] op_sel_hi:[1,0,1]
	v_pk_fma_f32 v[130:131], v[130:131], v[164:165], v[168:169] op_sel_hi:[1,0,1]
	v_cvt_pk_bf16_f32 v2, v134, v135
	v_cvt_pk_bf16_f32 v3, v132, v133
	v_cvt_pk_bf16_f32 v4, v130, v131
	v_cvt_pk_bf16_f32 v5, v128, v129
	global_store_dwordx4 v[162:163], v[2:5], off
	s_and_saveexec_b64 s[8:9], s[2:3]
	s_lshl_b32 s11, s37, 10
	s_add_i32 s11, s24, s11
	v_lshl_add_u32 v2, v145, 4, s11
	v_add_f32_e32 v0, v0, v1
	ds_write_b32 v2, v0
	s_or_b64 exec, exec, s[8:9]
	v_mul_f32_e32 v0, v119, v119
	v_mul_f32_e32 v1, v115, v115
	v_fmac_f32_e32 v0, v118, v118
	v_fmac_f32_e32 v1, v114, v114
	v_add_f32_e32 v0, v0, v1
	v_mul_f32_e32 v1, v117, v117
	v_mul_f32_e32 v2, v113, v113
	v_fmac_f32_e32 v1, v116, v116
	v_fmac_f32_e32 v2, v112, v112
	v_add_f32_e32 v1, v1, v2
	v_add_f32_e32 v0, v0, v1
	v_mul_f32_e32 v1, v71, v71
	v_mul_f32_e32 v2, v69, v69
	v_fmac_f32_e32 v1, v70, v70
	v_fmac_f32_e32 v2, v68, v68
	v_add_f32_e32 v1, v1, v2
	v_add_f32_e32 v0, v0, v1
	v_mul_f32_e32 v1, v67, v67
	v_mul_f32_e32 v2, v65, v65
	v_fmac_f32_e32 v1, v66, v66
	v_fmac_f32_e32 v2, v64, v64
	v_add_f32_e32 v1, v1, v2
	v_add_f32_e32 v0, v1, v0
	v_mov_b32_e32 v1, v0
	s_nop 1
	v_permlane16_swap_b32_e32 v0, v1
	v_add_f32_e32 v0, v0, v1
	v_mov_b32_e32 v1, v0
	s_nop 1
	v_permlane32_swap_b32_e32 v0, v1
	s_and_saveexec_b64 s[8:9], s[2:3]
	s_lshl_b32 s11, s37, 10
	s_add_i32 s11, s24, s11
	v_lshl_add_u32 v2, v145, 4, s11
	v_add_f32_e32 v0, v0, v1
	ds_write_b32 v2, v0 offset:256
	s_or_b64 exec, exec, s[8:9]
	v_mul_f32_e32 v0, v137, v137
	v_mul_f32_e32 v1, v109, v109
	v_fmac_f32_e32 v0, v136, v136
	v_fmac_f32_e32 v1, v108, v108
	v_add_f32_e32 v0, v0, v1
	v_mul_f32_e32 v1, v111, v111
	v_mul_f32_e32 v2, v107, v107
	v_fmac_f32_e32 v1, v110, v110
; #define LAS __attribute__((address_space(3)))
;     __device__ __forceinline__ void stats(const f32x4 (&v)[2][2][4][2], const Unit& u, int wr, int wc, int fr, int fq, LAS unsigned char* lds, int wid, int lane, int which, float c) const {
;     ...
; #pragma unroll
;         for (int ai = 0; ai < 2; ++ai)
; #pragma unroll
;             for (int m = 0; m < 4; ++m) { float q = 0.f;
; #pragma unroll
;                 for (int bj = 0; bj < 2; ++bj)
; #pragma unroll
;                     for (int n = 0; n < 2; ++n) { const f32x4 x = v[ai][bj][m][n]; q += (x[0] * x[0] + x[1] * x[1]) + (x[2] * x[2] + x[3] * x[3]); }
;                 { const unsigned uq = __float_as_uint(q); const auto r_ = __builtin_amdgcn_permlane16_swap(uq, uq, false, false); q = __uint_as_float(r_[0]) + __uint_as_float(r_[1]); }
;                 { const unsigned uq = __float_as_uint(q); const auto r_ = __builtin_amdgcn_permlane32_swap(uq, uq, false, false); q = __uint_as_float(r_[0]) + __uint_as_float(r_[1]); }
;                 if (fq == 0) P[(ai * HALF + wr * 64 + m * 16 + fr) * 4 + wc] = q; }
;         asm volatile("s_waitcnt lgkmcnt(0)" ::: "memory"); __builtin_amdgcn_s_barrier(); asm volatile("" ::: "memory");
;         const int row = wid * 32 + (lane & 31);
;         float* slot = slots + ((size_t)(which * 64 + u.pm) * BM + row) * 4;
;         unsigned* c0 = cnt + (size_t)(which * 64 + u.pm) * 64;
;         if (lane < 32) { const f32x4 p4 = *(const LAS f32x4*)(P + row * 4); __hip_atomic_store(slot + u.pn, (p4[0] + p4[1]) + (p4[2] + p4[3]), __ATOMIC_RELAXED, __HIP_MEMORY_SCOPE_AGENT); }
;         asm volatile("s_waitcnt vmcnt(0)" ::: "memory");
;         if (lane == 0) (void)__hip_atomic_fetch_add(c0, 1u, __ATOMIC_RELAXED, __HIP_MEMORY_SCOPE_AGENT);
;         if (wid == 0) { unsigned sp = 0u;
;             while ((unsigned)__builtin_amdgcn_readfirstlane(__hip_atomic_load(c0, __ATOMIC_RELAXED, __HIP_MEMORY_SCOPE_AGENT)) < 32u) { __builtin_amdgcn_s_sleep(1); if (++sp > (1u << 20)) break; }
;             __builtin_amdgcn_fence(__ATOMIC_ACQUIRE, "agent"); }
;         asm volatile("s_waitcnt vmcnt(0) lgkmcnt(0)" ::: "memory"); __builtin_amdgcn_s_barrier(); asm volatile("" ::: "memory");
	v_fmac_f32_e32 v2, v106, v106
	v_add_f32_e32 v1, v1, v2
	v_add_f32_e32 v0, v0, v1
	v_mul_f32_e32 v1, v59, v59
	v_mul_f32_e32 v2, v57, v57
	v_fmac_f32_e32 v1, v58, v58
	v_fmac_f32_e32 v2, v56, v56
	v_add_f32_e32 v1, v1, v2
	v_add_f32_e32 v0, v0, v1
	v_mul_f32_e32 v1, v51, v51
	v_mul_f32_e32 v2, v49, v49
	v_fmac_f32_e32 v1, v50, v50
	v_fmac_f32_e32 v2, v48, v48
	v_add_f32_e32 v1, v1, v2
	v_add_f32_e32 v0, v1, v0
	v_mov_b32_e32 v1, v0
	s_nop 1
	v_permlane16_swap_b32_e32 v0, v1
	v_add_f32_e32 v0, v0, v1
	v_mov_b32_e32 v1, v0
	s_nop 1
	v_permlane32_swap_b32_e32 v0, v1
	s_and_saveexec_b64 s[8:9], s[2:3]
	s_lshl_b32 s11, s37, 10
	s_add_i32 s11, s24, s11
	v_lshl_add_u32 v2, v145, 4, s11
	v_add_f32_e32 v0, v0, v1
	ds_write_b32 v2, v0 offset:512
	s_or_b64 exec, exec, s[8:9]
	v_mul_f32_e32 v0, v141, v141
	v_mul_f32_e32 v1, v103, v103
	v_fmac_f32_e32 v0, v140, v140
	v_fmac_f32_e32 v1, v102, v102
	v_add_f32_e32 v0, v0, v1
	v_mul_f32_e32 v1, v139, v139
	v_mul_f32_e32 v2, v101, v101
	v_fmac_f32_e32 v1, v138, v138
	v_fmac_f32_e32 v2, v100, v100
	v_add_f32_e32 v1, v1, v2
	v_add_f32_e32 v0, v0, v1
	v_mul_f32_e32 v1, v43, v43
	v_mul_f32_e32 v2, v41, v41
	v_fmac_f32_e32 v1, v42, v42
	v_fmac_f32_e32 v2, v40, v40
	v_add_f32_e32 v1, v1, v2
	v_add_f32_e32 v0, v0, v1
	v_mul_f32_e32 v1, v35, v35
	v_mul_f32_e32 v2, v33, v33
	v_fmac_f32_e32 v1, v34, v34
	v_fmac_f32_e32 v2, v32, v32
	v_add_f32_e32 v1, v1, v2
	v_add_f32_e32 v0, v1, v0
	v_mov_b32_e32 v1, v0
	s_nop 1
	v_permlane16_swap_b32_e32 v0, v1
	v_add_f32_e32 v0, v0, v1
	v_mov_b32_e32 v1, v0
	s_nop 1
	v_permlane32_swap_b32_e32 v0, v1
	s_and_saveexec_b64 s[8:9], s[2:3]
	s_lshl_b32 s11, s37, 10
	s_add_i32 s11, s24, s11
	v_lshl_add_u32 v2, v145, 4, s11
	v_add_f32_e32 v0, v0, v1
	ds_write_b32 v2, v0 offset:768
	s_or_b64 exec, exec, s[8:9]
	v_mul_f32_e32 v0, v95, v95
	v_mul_f32_e32 v1, v143, v143
	v_fmac_f32_e32 v0, v94, v94
	v_fmac_f32_e32 v1, v142, v142
	v_add_f32_e32 v0, v0, v1
	v_mul_f32_e32 v1, v93, v93
	v_mul_f32_e32 v2, v91, v91
	v_fmac_f32_e32 v1, v92, v92
	v_fmac_f32_e32 v2, v90, v90
	v_add_f32_e32 v1, v1, v2
	v_add_f32_e32 v0, v0, v1
	v_mul_f32_e32 v1, v31, v31
	v_mul_f32_e32 v2, v29, v29
	v_fmac_f32_e32 v1, v30, v30
	v_fmac_f32_e32 v2, v28, v28
	v_add_f32_e32 v1, v1, v2
	v_add_f32_e32 v0, v0, v1
	v_mul_f32_e32 v1, v27, v27
	v_mul_f32_e32 v2, v25, v25
	v_fmac_f32_e32 v1, v26, v26
	v_fmac_f32_e32 v2, v24, v24
	v_add_f32_e32 v1, v1, v2
	v_add_f32_e32 v0, v1, v0
	v_mov_b32_e32 v1, v0
	s_nop 1
	v_permlane16_swap_b32_e32 v0, v1
	v_add_f32_e32 v0, v0, v1
	v_mov_b32_e32 v1, v0
	s_nop 1
	v_permlane32_swap_b32_e32 v0, v1
	s_and_saveexec_b64 s[8:9], s[2:3]
	s_lshl_b32 s11, s37, 10
	s_add_i32 s11, s24, s11
	v_lshl_add_u32 v2, v145, 4, s11
	v_add_f32_e32 v0, v0, v1
	ds_write_b32 v2, v0 offset:2048
	s_or_b64 exec, exec, s[8:9]
	v_mul_f32_e32 v0, v99, v99
	v_mul_f32_e32 v1, v79, v79
	v_fmac_f32_e32 v0, v98, v98
	v_fmac_f32_e32 v1, v78, v78
	v_add_f32_e32 v0, v0, v1
	v_mul_f32_e32 v1, v77, v77
	v_mul_f32_e32 v2, v75, v75
	v_fmac_f32_e32 v1, v76, v76
	v_fmac_f32_e32 v2, v74, v74
	v_add_f32_e32 v1, v1, v2
	v_add_f32_e32 v0, v0, v1
	v_mul_f32_e32 v1, v23, v23
	v_mul_f32_e32 v2, v21, v21
	v_fmac_f32_e32 v1, v22, v22
	v_fmac_f32_e32 v2, v20, v20
	v_add_f32_e32 v1, v1, v2
	v_add_f32_e32 v0, v0, v1
	v_mul_f32_e32 v1, v19, v19
	v_mul_f32_e32 v2, v17, v17
	v_fmac_f32_e32 v1, v18, v18
	v_fmac_f32_e32 v2, v16, v16
	v_add_f32_e32 v1, v1, v2
	v_add_f32_e32 v0, v1, v0
	v_mov_b32_e32 v1, v0
	s_nop 1
	v_permlane16_swap_b32_e32 v0, v1
	v_add_f32_e32 v0, v0, v1
	v_mov_b32_e32 v1, v0
	s_nop 1
	v_permlane32_swap_b32_e32 v0, v1
	s_and_saveexec_b64 s[8:9], s[2:3]
	s_lshl_b32 s11, s37, 10
	s_add_i32 s11, s24, s11
	v_lshl_add_u32 v2, v145, 4, s11
	v_add_f32_e32 v0, v0, v1
	ds_write_b32 v2, v0 offset:2304
	s_or_b64 exec, exec, s[8:9]
	v_mul_f32_e32 v0, v63, v63
	v_mul_f32_e32 v1, v61, v61
	v_fmac_f32_e32 v0, v62, v62
	v_fmac_f32_e32 v1, v60, v60
	v_add_f32_e32 v0, v0, v1
	v_mul_f32_e32 v1, v55, v55
	v_mul_f32_e32 v2, v53, v53
	v_fmac_f32_e32 v1, v54, v54
	v_fmac_f32_e32 v2, v52, v52
	v_add_f32_e32 v1, v1, v2
	v_add_f32_e32 v0, v0, v1
	v_mul_f32_e32 v1, v15, v15
	v_mul_f32_e32 v2, v13, v13
	v_fmac_f32_e32 v1, v14, v14
	v_fmac_f32_e32 v2, v12, v12
	v_add_f32_e32 v1, v1, v2
	v_add_f32_e32 v0, v0, v1
	v_mul_f32_e32 v1, v11, v11
	v_mul_f32_e32 v2, v9, v9
	v_fmac_f32_e32 v1, v10, v10
	v_fmac_f32_e32 v2, v8, v8
	v_add_f32_e32 v1, v1, v2
	v_add_f32_e32 v0, v1, v0
	v_mov_b32_e32 v1, v0
	s_nop 1
	v_permlane16_swap_b32_e32 v0, v1
	v_add_f32_e32 v0, v0, v1
	v_mov_b32_e32 v1, v0
	s_nop 1
	v_permlane32_swap_b32_e32 v0, v1
	s_and_saveexec_b64 s[8:9], s[2:3]
	s_lshl_b32 s11, s37, 10
	s_add_i32 s11, s24, s11
	v_lshl_add_u32 v2, v145, 4, s11
	v_add_f32_e32 v0, v0, v1
	ds_write_b32 v2, v0 offset:2560
	s_or_b64 exec, exec, s[8:9]
	v_mul_f32_e32 v0, v47, v47
	v_mul_f32_e32 v1, v45, v45
	v_fmac_f32_e32 v0, v46, v46
	v_fmac_f32_e32 v1, v44, v44
	v_add_f32_e32 v0, v0, v1
	v_mul_f32_e32 v1, v39, v39
	v_mul_f32_e32 v2, v37, v37
	v_fmac_f32_e32 v1, v38, v38
	v_fmac_f32_e32 v2, v36, v36
	v_add_f32_e32 v1, v1, v2
	v_add_f32_e32 v0, v0, v1
	v_mul_f32_e32 v1, v135, v135
	v_mul_f32_e32 v2, v133, v133
	v_fmac_f32_e32 v1, v134, v134
	v_fmac_f32_e32 v2, v132, v132
	v_add_f32_e32 v1, v1, v2
	v_add_f32_e32 v0, v0, v1
	v_mul_f32_e32 v1, v131, v131
	v_mul_f32_e32 v2, v129, v129
	v_fmac_f32_e32 v1, v130, v130
	v_fmac_f32_e32 v2, v128, v128
	v_add_f32_e32 v1, v1, v2
	v_add_f32_e32 v0, v1, v0
	v_mov_b32_e32 v1, v0
	s_nop 1
	v_permlane16_swap_b32_e32 v0, v1
	v_add_f32_e32 v0, v0, v1
	v_mov_b32_e32 v1, v0
	s_nop 1
	v_permlane32_swap_b32_e32 v0, v1
	s_and_saveexec_b64 s[8:9], s[2:3]
	s_lshl_b32 s2, s37, 10
	s_add_i32 s24, s24, s2
	v_lshl_add_u32 v2, v145, 4, s24
	v_add_f32_e32 v0, v0, v1
	ds_write_b32 v2, v0 offset:2816
	s_or_b64 exec, exec, s[8:9]
	s_add_i32 s2, s16, 64
	s_ashr_i32 s3, s2, 31
	s_lshl_b64 s[8:9], s[2:3], 12
	s_waitcnt lgkmcnt(0)
	s_barrier
	s_add_u32 s8, s25, s8
	s_addc_u32 s9, s26, s9
	v_lshl_add_u64 v[0:1], s[8:9], 0, v[150:151]
	s_and_saveexec_b64 s[8:9], s[4:5]
	s_cbranch_execz .LBB0_359
	ds_read_b128 v[2:5], v167
	s_ashr_i32 s11, s10, 31
	v_lshl_add_u64 v[6:7], s[10:11], 2, v[0:1]
	s_waitcnt lgkmcnt(0)
	v_mov_b32_e32 v150, v3
	v_mov_b32_e32 v151, v4
	v_mov_b32_e32 v3, v5
	v_pk_add_f32 v[2:3], v[150:151], v[2:3]
	s_nop 0
	v_pk_add_f32 v[2:3], v[2:3], v[2:3] op_sel:[0,1] op_sel_hi:[1,0]
	global_store_dword v[6:7], v2, off sc1
